# v77 base + LRU scan: sigmoid rcp ops moved under ds_bpermute latency + batched first-barrier census loads
# baseline (speedup 1.0000x reference)
.LBB0_409:
	ds_read_b128 v[60:63], v51
	ds_read_b128 v[64:67], v51 offset:64
	ds_read_u16_d16_hi v232, v52
	ds_read_u16_d16_hi v233, v52 offset:272
	ds_read_u16_d16_hi v234, v52 offset:544
	ds_read_u16_d16_hi v235, v52 offset:816
	ds_read_u16_d16_hi v236, v157
	ds_read_u16_d16_hi v237, v157 offset:256
	ds_read_u16_d16_hi v238, v157 offset:512
	ds_read_u16_d16_hi v239, v157 offset:768
	s_waitcnt lgkmcnt(9)
	v_mfma_f32_16x16x32_bf16 v[36:39], v[60:63], v[0:3], 0
	v_mfma_f32_16x16x32_bf16 v[56:59], v[60:63], v[8:11], 0
	ds_read_b128 v[60:63], v51 offset:128
	s_waitcnt lgkmcnt(9)
	v_mfma_f32_16x16x32_bf16 v[36:39], v[64:67], v[4:7], v[36:39]
	v_mfma_f32_16x16x32_bf16 v[56:59], v[64:67], v[12:15], v[56:59]
	ds_read_b128 v[64:67], v51 offset:192
	s_waitcnt lgkmcnt(1)
	v_mfma_f32_16x16x32_bf16 v[36:39], v[60:63], v[16:19], v[36:39]
	v_mfma_f32_16x16x32_bf16 v[56:59], v[60:63], v[24:27], v[56:59]
	s_waitcnt lgkmcnt(0)
	v_mfma_f32_16x16x32_bf16 v[36:39], v[64:67], v[20:23], v[36:39]
	v_mfma_f32_16x16x32_bf16 v[56:59], v[64:67], v[28:31], v[56:59]
	v_add_u32_e32 v51, 0x1100, v51
	v_add_u32_e32 v52, 0x1100, v52
	v_add_u32_e32 v157, 0x1000, v157
	v_pk_mul_f32 v[230:231], v[236:237], v[240:241]
	v_pk_mul_f32 v[216:217], v[238:239], v[240:241]
	v_exp_f32_e32 v230, v230
	v_exp_f32_e32 v231, v231
	v_exp_f32_e32 v216, v216
	v_exp_f32_e32 v217, v217
	v_pk_fma_f32 v[212:213], v[36:37], v[240:241], v[242:243]
	v_pk_fma_f32 v[214:215], v[38:39], v[240:241], v[242:243]
	v_pk_fma_f32 v[220:221], v[56:57], v[240:241], v[244:245]
	v_pk_fma_f32 v[222:223], v[58:59], v[240:241], v[244:245]
	v_exp_f32_e32 v212, v212
	v_exp_f32_e32 v213, v213
	v_exp_f32_e32 v214, v214
	v_exp_f32_e32 v215, v215
	v_exp_f32_e32 v220, v220
	v_exp_f32_e32 v221, v221
	v_exp_f32_e32 v222, v222
	v_exp_f32_e32 v223, v223
	v_pk_add_f32 v[212:213], v[212:213], 1.0 op_sel_hi:[1,0]
	v_pk_add_f32 v[214:215], v[214:215], 1.0 op_sel_hi:[1,0]
	v_pk_add_f32 v[220:221], v[220:221], 1.0 op_sel_hi:[1,0]
	v_pk_add_f32 v[222:223], v[222:223], 1.0 op_sel_hi:[1,0]
	v_rcp_f32_e32 v212, v212
	v_rcp_f32_e32 v213, v213
	v_rcp_f32_e32 v214, v214
	v_rcp_f32_e32 v215, v215
	v_rcp_f32_e32 v220, v220
	v_rcp_f32_e32 v221, v221
	v_rcp_f32_e32 v222, v222
	v_rcp_f32_e32 v223, v223
	v_pk_mul_f32 v[226:227], v[212:213], v[246:247]
	v_pk_mul_f32 v[228:229], v[214:215], v[246:247]
	v_pk_mul_f32 v[220:221], v[220:221], v[232:233]
	v_pk_mul_f32 v[222:223], v[222:223], v[234:235]
	v_exp_f32_e32 v226, v226
	v_exp_f32_e32 v227, v227
	v_exp_f32_e32 v228, v228
	v_exp_f32_e32 v229, v229
	v_pk_fma_f32 v[166:167], v[226:227], v[226:227], 1.0 op_sel_hi:[1,1,0] neg_lo:[1,0,0] neg_hi:[1,0,0]
	v_pk_fma_f32 v[168:169], v[228:229], v[228:229], 1.0 op_sel_hi:[1,1,0] neg_lo:[1,0,0] neg_hi:[1,0,0]
	v_sqrt_f32_e32 v166, v166
	v_sqrt_f32_e32 v167, v167
	v_sqrt_f32_e32 v168, v168
	v_sqrt_f32_e32 v169, v169
	v_pk_mul_f32 v[166:167], v[166:167], v[220:221]
	v_pk_mul_f32 v[168:169], v[168:169], v[222:223]
	v_fmac_f32_e32 v167, v227, v166
	v_mul_f32_e32 v227, v227, v226
	v_fmac_f32_e32 v168, v228, v167
	v_mul_f32_e32 v228, v228, v227
	v_fmac_f32_e32 v169, v229, v168
	v_mul_f32_e32 v229, v229, v228
	ds_bpermute_b32 v40, v47, v229
	ds_bpermute_b32 v41, v47, v169
	v_pk_add_f32 v[230:231], v[230:231], 1.0 op_sel_hi:[1,0]
	v_pk_add_f32 v[216:217], v[216:217], 1.0 op_sel_hi:[1,0]
	v_rcp_f32_e32 v230, v230
	v_rcp_f32_e32 v231, v231
	v_rcp_f32_e32 v216, v216
	v_rcp_f32_e32 v217, v217
	s_waitcnt lgkmcnt(0)
	v_mul_f32_e32 v40, v229, v40
	v_fma_f32 v41, v229, v41, v169
	v_cndmask_b32_e32 v225, v40, v229, vcc
	v_cndmask_b32_e32 v126, v41, v169, vcc
	ds_bpermute_b32 v40, v49, v225
	ds_bpermute_b32 v41, v49, v126
	s_waitcnt lgkmcnt(0)
	v_mul_f32_e32 v40, v225, v40
	v_fma_f32 v41, v225, v41, v126
	v_cndmask_b32_e64 v185, v225, v40, s[38:39]
	v_cndmask_b32_e64 v186, v126, v41, s[38:39]
	v_fmac_f32_e32 v186, v44, v185
	ds_bpermute_b32 v34, v47, v186
	ds_bpermute_b32 v35, v47, v185
	ds_bpermute_b32 v187, v50, v186
	ds_bpermute_b32 v156, v50, v185
	s_waitcnt lgkmcnt(0)
	v_cndmask_b32_e32 v34, v34, v44, vcc
	v_cndmask_b32_e64 v35, v35, 1.0, vcc
	v_mul_f32_e32 v35, v43, v35
	v_mov_b32_e32 v44, v187
	v_mul_f32_e32 v43, v43, v156
	v_pk_fma_f32 v[166:167], v[226:227], v[34:35], v[166:167] op_sel_hi:[1,0,1]
	v_pk_fma_f32 v[168:169], v[228:229], v[34:35], v[168:169] op_sel_hi:[1,0,1]
	v_pk_mul_f32 v[226:227], v[226:227], v[34:35] op_sel:[0,1] op_sel_hi:[1,1]
	v_pk_mul_f32 v[228:229], v[228:229], v[34:35] op_sel:[0,1] op_sel_hi:[1,1]
	v_pk_mul_f32 v[166:167], v[166:167], v[230:231]
	v_pk_mul_f32 v[168:169], v[168:169], v[216:217]
	v_pk_mul_f32 v[226:227], v[226:227], v[230:231]
	v_pk_mul_f32 v[228:229], v[228:229], v[216:217]
	v_cvt_pk_bf16_f32 v54, v166, v167
	v_cvt_pk_bf16_f32 v55, v168, v169
	v_cvt_pk_bf16_f32 v222, v226, v227
	v_cvt_pk_bf16_f32 v223, v228, v229
	global_store_short v170, v54, s[62:63]
	global_store_short_d16_hi v170, v54, s[62:63] offset:2048
	global_store_short v171, v55, s[62:63]
	global_store_short_d16_hi v171, v55, s[62:63] offset:2048
	global_store_short v170, v222, s[90:91]
	global_store_short_d16_hi v170, v222, s[90:91] offset:2048
	global_store_short v171, v223, s[90:91]
	global_store_short_d16_hi v171, v223, s[90:91] offset:2048
	v_add_u32_e32 v170, 0x8000, v170
	v_add_u32_e32 v171, 0x8000, v171
	s_add_i32 s5, s5, 1
	s_cmp_lt_i32 s5, s68
	s_cbranch_scc1 .LBB0_409
	v_cmp_eq_u32_e32 vcc, 0, v42
	s_and_saveexec_b64 s[0:1], vcc
	s_cbranch_execz .LBB0_346
	s_branch .LBB0_412
